# accumulator zeroing with v_mov_b64 (64 instead of 128 per tile), dattn S-init broadcast with v_mov_b64, dattn K-fragment ds_reads issued before the LDS-DMA block, compiler's redundant mid-step vmcnt(0
# speedup vs baseline: 1.0024x; 1.0004x over previous
; template <class Epi, class Sched, bool ALIGN_EPI = false, bool SP2 = false>
; __device__ __forceinline__ void gemm_phase(PG8_LAS unsigned char* lds, const Gemm g, const Sched& S, const Epi& E, const int tid) {
;     ...
;     f32x4 acc[2][2][4][2];
; #pragma unroll
;     for (int a = 0; a < 2; ++a)
; #pragma unroll
;         for (int b = 0; b < 2; ++b)
; #pragma unroll
;             for (int m = 0; m < 4; ++m)
; #pragma unroll
;                 for (int n = 0; n < 2; ++n) acc[a][b][m][n] = (f32x4){0.f, 0.f, 0.f, 0.f};
;     ...
; #pragma unroll
;         for (int a = 0; a < 2; ++a)
; #pragma unroll
;             for (int b = 0; b < 2; ++b)
; #pragma unroll
;                 for (int m = 0; m < 4; ++m)
; #pragma unroll
;                     for (int n = 0; n < 2; ++n) acc[a][b][m][n] = (f32x4){0.f, 0.f, 0.f, 0.f};
.LBB0_278:
	s_ashr_i32 s17, s16, 31
	s_lshl_b64 s[18:19], s[16:17], 19
	s_add_u32 s18, s1, s18
	s_addc_u32 s19, s30, s19
	s_and_b64 s[20:21], s[2:3], exec
	s_cselect_b32 s17, s19, s25
	s_cselect_b32 s54, s18, s24
	s_ashr_i32 s15, s14, 31
	s_lshl_b64 s[20:21], s[14:15], 19
	s_add_u32 s20, s31, s20
	s_addc_u32 s21, s33, s21
	s_and_b64 s[28:29], s[2:3], exec
	s_cselect_b32 s15, s21, s27
	s_cselect_b32 s55, s20, s26
	s_add_u32 s24, s24, 0x40080
	s_addc_u32 s25, s25, 0
	s_add_u32 s56, s26, 0x100
	v_mov_b64_e32 v[0:1], 0
	v_mov_b64_e32 v[2:3], 0
	v_mov_b64_e32 v[4:5], 0
	v_mov_b64_e32 v[6:7], 0
	v_mov_b64_e32 v[8:9], 0
	v_mov_b64_e32 v[10:11], 0
	v_mov_b64_e32 v[12:13], 0
	v_mov_b64_e32 v[14:15], 0
	v_mov_b64_e32 v[16:17], 0
	v_mov_b64_e32 v[18:19], 0
	v_mov_b64_e32 v[20:21], 0
	v_mov_b64_e32 v[22:23], 0
	v_mov_b64_e32 v[24:25], 0
	v_mov_b64_e32 v[26:27], 0
	v_mov_b64_e32 v[28:29], 0
	v_mov_b64_e32 v[30:31], 0
	v_mov_b64_e32 v[32:33], 0
	v_mov_b64_e32 v[34:35], 0
	v_mov_b64_e32 v[36:37], 0
	v_mov_b64_e32 v[38:39], 0
	v_mov_b64_e32 v[40:41], 0
	v_mov_b64_e32 v[42:43], 0
	v_mov_b64_e32 v[44:45], 0
	v_mov_b64_e32 v[46:47], 0
	v_mov_b64_e32 v[48:49], 0
	v_mov_b64_e32 v[50:51], 0
	v_mov_b64_e32 v[52:53], 0
	v_mov_b64_e32 v[54:55], 0
	v_mov_b64_e32 v[56:57], 0
	v_mov_b64_e32 v[58:59], 0
	v_mov_b64_e32 v[60:61], 0
	v_mov_b64_e32 v[62:63], 0
	v_mov_b64_e32 v[64:65], 0
	v_mov_b64_e32 v[66:67], 0
	v_mov_b64_e32 v[68:69], 0
	v_mov_b64_e32 v[70:71], 0
	v_mov_b64_e32 v[72:73], 0
	v_mov_b64_e32 v[74:75], 0
	v_mov_b64_e32 v[76:77], 0
	v_mov_b64_e32 v[78:79], 0
	v_mov_b64_e32 v[80:81], 0
	v_mov_b64_e32 v[82:83], 0
	v_mov_b64_e32 v[84:85], 0
	v_mov_b64_e32 v[86:87], 0
	v_mov_b64_e32 v[88:89], 0
	v_mov_b64_e32 v[90:91], 0
	v_mov_b64_e32 v[92:93], 0
	v_mov_b64_e32 v[94:95], 0
	v_mov_b64_e32 v[96:97], 0
	v_mov_b64_e32 v[98:99], 0
	v_mov_b64_e32 v[100:101], 0
	v_mov_b64_e32 v[102:103], 0
	v_mov_b64_e32 v[104:105], 0
	v_mov_b64_e32 v[106:107], 0
	v_mov_b64_e32 v[108:109], 0
	v_mov_b64_e32 v[110:111], 0
	v_mov_b64_e32 v[112:113], 0
	v_mov_b64_e32 v[114:115], 0
	v_mov_b64_e32 v[116:117], 0
	v_mov_b64_e32 v[118:119], 0
	v_mov_b64_e32 v[120:121], 0
	v_mov_b64_e32 v[122:123], 0
	v_mov_b64_e32 v[124:125], 0
	v_mov_b64_e32 v[126:127], 0
	s_addc_u32 s57, s27, 0
	s_mov_b32 s58, -2

; template <class Epi, class Sched, bool ALIGN_EPI = false, bool SP2 = false>
; __device__ __forceinline__ void gemm_phase(PG8_LAS unsigned char* lds, const Gemm g, const Sched& S, const Epi& E, const int tid) {
;     ...
;     f32x4 acc[2][2][4][2];
; #pragma unroll
;     for (int a = 0; a < 2; ++a)
; #pragma unroll
;         for (int b = 0; b < 2; ++b)
; #pragma unroll
;             for (int m = 0; m < 4; ++m)
; #pragma unroll
;                 for (int n = 0; n < 2; ++n) acc[a][b][m][n] = (f32x4){0.f, 0.f, 0.f, 0.f};
;     ...
; #pragma unroll
;         for (int a = 0; a < 2; ++a)
; #pragma unroll
;             for (int b = 0; b < 2; ++b)
; #pragma unroll
;                 for (int m = 0; m < 4; ++m)
; #pragma unroll
;                     for (int n = 0; n < 2; ++n) acc[a][b][m][n] = (f32x4){0.f, 0.f, 0.f, 0.f};
.LBB0_352:
	s_add_u32 s57, s24, 0x100
	v_mov_b64_e32 v[0:1], 0
	v_mov_b64_e32 v[2:3], 0
	v_mov_b64_e32 v[4:5], 0
	v_mov_b64_e32 v[6:7], 0
	v_mov_b64_e32 v[8:9], 0
	v_mov_b64_e32 v[10:11], 0
	v_mov_b64_e32 v[12:13], 0
	v_mov_b64_e32 v[14:15], 0
	v_mov_b64_e32 v[16:17], 0
	v_mov_b64_e32 v[18:19], 0
	v_mov_b64_e32 v[20:21], 0
	v_mov_b64_e32 v[22:23], 0
	v_mov_b64_e32 v[24:25], 0
	v_mov_b64_e32 v[26:27], 0
	v_mov_b64_e32 v[28:29], 0
	v_mov_b64_e32 v[30:31], 0
	v_mov_b64_e32 v[32:33], 0
	v_mov_b64_e32 v[34:35], 0
	v_mov_b64_e32 v[36:37], 0
	v_mov_b64_e32 v[38:39], 0
	v_mov_b64_e32 v[40:41], 0
	v_mov_b64_e32 v[42:43], 0
	v_mov_b64_e32 v[44:45], 0
	v_mov_b64_e32 v[46:47], 0
	v_mov_b64_e32 v[48:49], 0
	v_mov_b64_e32 v[50:51], 0
	v_mov_b64_e32 v[52:53], 0
	v_mov_b64_e32 v[54:55], 0
	v_mov_b64_e32 v[56:57], 0
	v_mov_b64_e32 v[58:59], 0
	v_mov_b64_e32 v[60:61], 0
	v_mov_b64_e32 v[62:63], 0
	v_mov_b64_e32 v[64:65], 0
	v_mov_b64_e32 v[66:67], 0
	v_mov_b64_e32 v[68:69], 0
	v_mov_b64_e32 v[70:71], 0
	v_mov_b64_e32 v[72:73], 0
	v_mov_b64_e32 v[74:75], 0
	v_mov_b64_e32 v[76:77], 0
	v_mov_b64_e32 v[78:79], 0
	v_mov_b64_e32 v[80:81], 0
	v_mov_b64_e32 v[82:83], 0
	v_mov_b64_e32 v[84:85], 0
	v_mov_b64_e32 v[86:87], 0
	v_mov_b64_e32 v[88:89], 0
	v_mov_b64_e32 v[90:91], 0
	v_mov_b64_e32 v[92:93], 0
	v_mov_b64_e32 v[94:95], 0
	v_mov_b64_e32 v[96:97], 0
	v_mov_b64_e32 v[98:99], 0
	v_mov_b64_e32 v[100:101], 0
	v_mov_b64_e32 v[102:103], 0
	v_mov_b64_e32 v[104:105], 0
	v_mov_b64_e32 v[106:107], 0
	v_mov_b64_e32 v[108:109], 0
	v_mov_b64_e32 v[110:111], 0
	v_mov_b64_e32 v[112:113], 0
	v_mov_b64_e32 v[114:115], 0
	v_mov_b64_e32 v[116:117], 0
	v_mov_b64_e32 v[118:119], 0
	v_mov_b64_e32 v[120:121], 0
	v_mov_b64_e32 v[122:123], 0
	v_mov_b64_e32 v[124:125], 0
	v_mov_b64_e32 v[126:127], 0
	s_addc_u32 s58, s25, 0
	s_mov_b32 s59, -2
	s_waitcnt lgkmcnt(0)

; template <class Epi, class Sched, bool ALIGN_EPI = false, bool SP2 = false>
; __device__ __forceinline__ void gemm_phase(PG8_LAS unsigned char* lds, const Gemm g, const Sched& S, const Epi& E, const int tid) {
;     ...
;     f32x4 acc[2][2][4][2];
; #pragma unroll
;     for (int a = 0; a < 2; ++a)
; #pragma unroll
;         for (int b = 0; b < 2; ++b)
; #pragma unroll
;             for (int m = 0; m < 4; ++m)
; #pragma unroll
;                 for (int n = 0; n < 2; ++n) acc[a][b][m][n] = (f32x4){0.f, 0.f, 0.f, 0.f};
;     ...
; #pragma unroll
;         for (int a = 0; a < 2; ++a)
; #pragma unroll
;             for (int b = 0; b < 2; ++b)
; #pragma unroll
;                 for (int m = 0; m < 4; ++m)
; #pragma unroll
;                     for (int n = 0; n < 2; ++n) acc[a][b][m][n] = (f32x4){0.f, 0.f, 0.f, 0.f};
.LBB0_436:
	s_ashr_i32 s25, s24, 31
	s_lshl_b64 s[26:27], s[24:25], 19
	s_add_u32 s26, s41, s26
	s_addc_u32 s27, s42, s27
	s_and_b64 s[28:29], s[2:3], exec
	s_cselect_b32 s0, s27, s31
	s_cselect_b32 s21, s26, s30
	s_ashr_i32 s23, s22, 31
	s_lshl_b64 s[28:29], s[22:23], 19
	s_add_u32 s28, s43, s28
	s_addc_u32 s29, s50, s29
	s_and_b64 s[36:37], s[2:3], exec
	s_cselect_b32 s23, s29, s35
	s_cselect_b32 s25, s28, s34
	s_add_u32 s30, s30, 0x40080
	s_addc_u32 s31, s31, 0
	s_add_u32 s33, s34, 0x100
	v_mov_b64_e32 v[0:1], 0
	v_mov_b64_e32 v[2:3], 0
	v_mov_b64_e32 v[4:5], 0
	v_mov_b64_e32 v[6:7], 0
	v_mov_b64_e32 v[8:9], 0
	v_mov_b64_e32 v[10:11], 0
	v_mov_b64_e32 v[12:13], 0
	v_mov_b64_e32 v[14:15], 0
	v_mov_b64_e32 v[16:17], 0
	v_mov_b64_e32 v[18:19], 0
	v_mov_b64_e32 v[20:21], 0
	v_mov_b64_e32 v[22:23], 0
	v_mov_b64_e32 v[24:25], 0
	v_mov_b64_e32 v[26:27], 0
	v_mov_b64_e32 v[28:29], 0
	v_mov_b64_e32 v[30:31], 0
	v_mov_b64_e32 v[32:33], 0
	v_mov_b64_e32 v[34:35], 0
	v_mov_b64_e32 v[36:37], 0
	v_mov_b64_e32 v[38:39], 0
	v_mov_b64_e32 v[40:41], 0
	v_mov_b64_e32 v[42:43], 0
	v_mov_b64_e32 v[44:45], 0
	v_mov_b64_e32 v[46:47], 0
	v_mov_b64_e32 v[48:49], 0
	v_mov_b64_e32 v[50:51], 0
	v_mov_b64_e32 v[52:53], 0
	v_mov_b64_e32 v[54:55], 0
	v_mov_b64_e32 v[56:57], 0
	v_mov_b64_e32 v[58:59], 0
	v_mov_b64_e32 v[60:61], 0
	v_mov_b64_e32 v[62:63], 0
	v_mov_b64_e32 v[64:65], 0
	v_mov_b64_e32 v[66:67], 0
	v_mov_b64_e32 v[68:69], 0
	v_mov_b64_e32 v[70:71], 0
	v_mov_b64_e32 v[72:73], 0
	v_mov_b64_e32 v[74:75], 0
	v_mov_b64_e32 v[76:77], 0
	v_mov_b64_e32 v[78:79], 0
	v_mov_b64_e32 v[80:81], 0
	v_mov_b64_e32 v[82:83], 0
	v_mov_b64_e32 v[84:85], 0
	v_mov_b64_e32 v[86:87], 0
	v_mov_b64_e32 v[88:89], 0
	v_mov_b64_e32 v[90:91], 0
	v_mov_b64_e32 v[92:93], 0
	v_mov_b64_e32 v[94:95], 0
	v_mov_b64_e32 v[96:97], 0
	v_mov_b64_e32 v[98:99], 0
	v_mov_b64_e32 v[100:101], 0
	v_mov_b64_e32 v[102:103], 0
	v_mov_b64_e32 v[104:105], 0
	v_mov_b64_e32 v[106:107], 0
	v_mov_b64_e32 v[108:109], 0
	v_mov_b64_e32 v[110:111], 0
	v_mov_b64_e32 v[112:113], 0
	v_mov_b64_e32 v[114:115], 0
	v_mov_b64_e32 v[116:117], 0
	v_mov_b64_e32 v[118:119], 0
	v_mov_b64_e32 v[120:121], 0
	v_mov_b64_e32 v[122:123], 0
	v_mov_b64_e32 v[124:125], 0
	v_mov_b64_e32 v[126:127], 0
	s_addc_u32 s38, s35, 0
	s_mov_b32 s39, -2

; #define LAS __attribute__((address_space(3)))
; #define DA_DMAK(kt, slot) do { _Pragma("unroll") for (int i_ = 0; i_ < 2; ++i_) __builtin_amdgcn_global_load_lds((const unsigned*)(kbase + (size_t)((((kt) + rot) & 31) * 64) * NIN + dsrc[i_]), \
;         (LAS unsigned*)(lds + (slot) * 32768 + (2 * wid + i_) * 1024), 16, 0, 0); } while (0)
; #define DA_DMAV(kt, slot) do { _Pragma("unroll") for (int i_ = 0; i_ < 2; ++i_) __builtin_amdgcn_global_load_lds((const unsigned*)(kbase + 512 + (size_t)((((kt) + rot) & 31) * 64) * NIN + dsrc[i_]), \
;         (LAS unsigned*)(lds + (slot) * 32768 + 16384 + (2 * wid + i_) * 1024), 16, 0, 0); } while (0)
; #define DA_WAITBAR() asm volatile("s_waitcnt vmcnt(0) lgkmcnt(0)\n\ts_barrier" ::: "memory")
; __device__ __forceinline__ void dattn_unit(const Args& a, unsigned char* ws, LAS unsigned char* lds, int l, int unit, int tid, int wid, int lane, int dry) {
;     ...
;     const int qb = unit & 15, h = (unit >> 4) & 3, b = unit >> 6;
;     const int r32 = lane & 31, hi = lane >> 5, g1 = (lane >> 4) & 1, q4 = (lane & 15) >> 2, p4 = lane & 3;
;     const int t = wid & 1, rg = wid >> 1;
;     const int qw = qb * 128 + rg * 32;
;     bf16* P = (bf16*)(ws + WS_P);
;     const size_t tok = (size_t)b * SEQ + qw + r32;
;     const LAS float* tab = (const LAS float*)(lds + LDS_TAB) + h * 321;
;     const LAS float* misc = (const LAS float*)(lds + LDS_MISC);
;     bf16x8 qf[4];
; #pragma unroll
;     for (int d0 = 0; d0 < 4; ++d0) qf[d0] = *(const bf16x8*)(P + tok * NIN + 2048 + h * 128 + t * 64 + 16 * d0 + 8 * hi);
;     const bf16* kbase = P + (size_t)b * SEQ * NIN + 2560 + h * 128;
;     f32x16 O[4];
; #pragma unroll
;     for (int eb = 0; eb < 4; ++eb)
; #pragma unroll
;         for (int r = 0; r < 16; ++r) O[eb][r] = 0.f;
;     float lsum = 0.f;
;     const float bneg = tab[0], bpos = tab[320];
;     unsigned vp[4][2], kb[4];
; #pragma unroll
;     for (int c = 0; c < 4; ++c) { vp[c][0] = tr_base_perm(c, 0, lane); vp[c][1] = tr_base_perm(c, 1, lane); kb[c] = row_base(8 * t + 2 * c, lane); }
;     const int rot = 2 * qb;
;     int dsrc[2];
; #pragma unroll
;     for (int i = 0; i < 2; ++i) { const int p = (2 * wid + i) * 64 + lane, row = p >> 4, ch = (p & 15) ^ (((row & 3) << 2) | ((row >> 2) & 3)); dsrc[i] = row * NIN + ch * 8; }
;     ...
;     DA_DMAK(0, 0); DA_DMAV(0, 0); DA_DMAK(1, 1);
;     DA_WAITBAR();
;     DA_QK(0, 0, SA);
.LBB0_640:
	s_and_b32 s59, s52, 15
	s_ashr_i32 s56, s52, 6
	s_lshl_b32 s54, s59, 7
	s_and_b32 s10, s49, 15
	s_add_i32 s53, s54, s31
	s_ashr_i32 s57, s56, 31
	s_lshl_b32 s58, s10, 7
	v_mov_b32_e32 v20, v199
	v_mov_b32_e32 v0, v176
	s_bfe_u32 s12, s52, 0x20004
	s_lshl_b64 s[10:11], s[56:57], 11
	s_ashr_i32 s55, s53, 31
	s_add_u32 s10, s10, s53
	v_and_b32_e32 v203, 31, v20
	v_or_b32_e32 v0, s10, v203
	s_addc_u32 s11, s11, s55
	v_mad_u64_u32 v[0:1], s[60:61], v0, s37, v[178:179]
	s_mul_i32 s10, s12, 0x504
	v_mad_i32_i24 v1, s11, v177, v1
	s_lshl_b32 s12, s12, 8
	v_ashrrev_i32_e32 v202, 5, v20
	v_lshl_add_u64 v[0:1], v[0:1], 0, s[12:13]
	v_lshl_add_u64 v[180:181], v[0:1], 0, s[22:23]
	v_lshlrev_b32_e32 v182, 3, v202
	v_lshl_add_u64 v[0:1], v[180:181], 0, s[24:25]
	v_ashrrev_i32_e32 v183, 31, v182
	v_lshl_add_u64 v[0:1], v[182:183], 1, v[0:1]
	global_load_dwordx4 v[140:143], v[0:1], off
	global_load_dwordx4 v[136:139], v[0:1], off offset:32
	global_load_dwordx4 v[132:135], v[0:1], off offset:64
	global_load_dwordx4 v[128:131], v[0:1], off offset:96
	s_add_i32 s10, s71, s10
	v_mov_b32_e32 v0, s10
	ds_read2st64_b32 v[184:185], v0 offset1:5
	v_lshlrev_b32_e32 v0, 2, v20
	v_bfe_u32 v21, v20, 2, 2
	v_and_b32_e32 v12, 12, v0
	v_lshlrev_b32_e32 v0, 8, v20
	v_add_u32_e32 v14, s33, v202
	v_and_b32_e32 v13, 0x1f00, v0
	v_bitop3_b32 v0, v12, v14, v21 bitop3:0x36
	v_lshl_add_u32 v4, v0, 4, v13
	v_add_u32_e32 v0, 2, v14
	v_bitop3_b32 v0, v0, v12, v21 bitop3:0x1e
	v_lshl_add_u32 v5, v0, 4, v13
	v_add_u32_e32 v0, s34, v20
	v_ashrrev_i32_e32 v2, 4, v0
	s_mul_i32 s55, s56, 0xe00000
	v_lshlrev_b32_e32 v3, 2, v2
	s_mul_hi_i32 s11, s56, 0xe00000
	s_add_u32 s55, s50, s55
	v_and_b32_e32 v1, 15, v20
	v_and_b32_e32 v3, 12, v3
	v_bfe_u32 v6, v0, 6, 2
	s_addc_u32 s11, s51, s11
	v_bitop3_b32 v3, v3, v1, v6 bitop3:0x36
	v_mul_lo_u32 v2, v2, s40
	v_add_u32_e32 v0, 64, v0
	s_add_u32 s12, s55, s12
	v_lshl_or_b32 v186, v3, 3, v2
	v_ashrrev_i32_e32 v2, 4, v0
	s_addc_u32 s11, s11, 0
	v_lshlrev_b32_e32 v3, 2, v2
	s_add_u32 s12, s12, 0x1400
	v_and_b32_e32 v3, 12, v3
	v_bfe_u32 v0, v0, 6, 2
	s_addc_u32 s55, s11, 0
	v_bitop3_b32 v0, v3, v1, v0 bitop3:0x36
	v_mul_lo_u32 v1, v2, s40
	s_mul_i32 s59, s59, 0xe0000
	v_lshl_or_b32 v188, v0, 3, v1
	s_add_u32 s56, s12, s59
	v_ashrrev_i32_e32 v187, 31, v186
	s_addc_u32 s57, s55, 0
	v_lshlrev_b64 v[190:191], 1, v[186:187]
	v_ashrrev_i32_e32 v189, 31, v188
	s_mov_b32 m0, s41
	v_lshl_add_u64 v[0:1], s[56:57], 0, v[190:191]
	v_lshlrev_b64 v[192:193], 1, v[188:189]
	global_load_lds_dwordx4 v[0:1], off
	v_lshl_add_u64 v[2:3], s[56:57], 0, v[192:193]
	s_mov_b32 m0, s42
	v_lshl_add_u64 v[0:1], v[0:1], 0, s[26:27]
	global_load_lds_dwordx4 v[2:3], off
	s_mov_b32 m0, s43
	s_add_u32 s56, s56, 0x70000
	global_load_lds_dwordx4 v[0:1], off
	v_lshl_add_u64 v[0:1], v[2:3], 0, s[26:27]
	s_mov_b32 m0, s44
	s_addc_u32 s57, s57, 0
	global_load_lds_dwordx4 v[0:1], off
	v_lshl_add_u64 v[0:1], s[56:57], 0, v[190:191]
	s_mov_b32 m0, s45
	v_add_u32_e32 v214, s70, v4
	global_load_lds_dwordx4 v[0:1], off
	v_lshl_add_u64 v[0:1], s[56:57], 0, v[192:193]
	s_mov_b32 m0, s46
	v_add_u32_e32 v215, s70, v5
	global_load_lds_dwordx4 v[0:1], off
	s_waitcnt vmcnt(0) lgkmcnt(0)
	s_barrier
	ds_read_b128 v[0:3], v214
	ds_read_b128 v[4:7], v214 offset:8192
	s_waitcnt lgkmcnt(0)
	v_cndmask_b32_e64 v8, 0, v185, s[4:5]
	v_cndmask_b32_e64 v80, v8, v184, s[2:3]
	v_mov_b32_e32 v81, v80
	v_mov_b64_e32 v[82:83], v[80:81]
	v_mov_b64_e32 v[84:85], v[80:81]
	v_mov_b64_e32 v[86:87], v[80:81]
	v_mov_b64_e32 v[88:89], v[80:81]
	v_mov_b64_e32 v[90:91], v[80:81]
	v_mov_b64_e32 v[92:93], v[80:81]
	v_mov_b64_e32 v[94:95], v[80:81]
	v_add_u32_e32 v8, 4, v14
	v_bitop3_b32 v8, v8, v12, v21 bitop3:0x1e
	s_waitcnt vmcnt(0)
	v_mfma_f32_32x32x16_bf16 v[80:95], v[0:3], v[140:143], v[80:95]
	ds_read_b128 v[0:3], v215
	v_lshl_add_u32 v8, v8, 4, v13
	v_add_u32_e32 v216, s70, v8
	ds_read_b128 v[8:11], v215 offset:8192
	v_add_u32_e32 v14, 6, v14
	v_bitop3_b32 v12, v14, v12, v21 bitop3:0x1e
	v_lshl_add_u32 v12, v12, 4, v13
	s_waitcnt lgkmcnt(1)
	v_mfma_f32_32x32x16_bf16 v[80:95], v[0:3], v[136:139], v[80:95]
	ds_read_b128 v[0:3], v216
	v_add_u32_e32 v217, s70, v12
	ds_read_b128 v[12:15], v216 offset:8192
	v_lshrrev_b32_e32 v16, 3, v20
	v_and_b32_e32 v22, 2, v16
	ds_read_b128 v[16:19], v217 offset:8192
	v_bfe_u32 v23, v20, 1, 1
	s_waitcnt lgkmcnt(2)
	v_mfma_f32_32x32x16_bf16 v[80:95], v[0:3], v[132:135], v[80:95]
	ds_read_b128 v[0:3], v217
	v_lshlrev_b32_e32 v24, 10, v202
	s_waitcnt vmcnt(0) lgkmcnt(0)
	s_barrier
; __device__ __forceinline__ void dattn_unit(const Args& a, unsigned char* ws, LAS unsigned char* lds, int l, int unit, int tid, int wid, int lane, int dry) {
;     ...
;     f32x16 O[4];
; #pragma unroll
;     for (int eb = 0; eb < 4; ++eb)
; #pragma unroll
;         for (int r = 0; r < 16; ++r) O[eb][r] = 0.f;
;     float lsum = 0.f;
;     const float bneg = tab[0], bpos = tab[320];
;     unsigned vp[4][2], kb[4];
; #pragma unroll
;     for (int c = 0; c < 4; ++c) { vp[c][0] = tr_base_perm(c, 0, lane); vp[c][1] = tr_base_perm(c, 1, lane); kb[c] = row_base(8 * t + 2 * c, lane); }
;     const int rot = 2 * qb;
;     int dsrc[2];
; #pragma unroll
;     for (int i = 0; i < 2; ++i) { const int p = (2 * wid + i) * 64 + lane, row = p >> 4, ch = (p & 15) ^ (((row & 3) << 2) | ((row >> 2) & 3)); dsrc[i] = row * NIN + ch * 8; }
	v_mov_b32_e32 v213, 0
	v_lshl_add_u32 v212, v202, 4, s10
	s_mov_b32 s56, -2
	v_mov_b32_e32 v48, 0
	s_waitcnt lgkmcnt(0)
	v_mfma_f32_32x32x16_bf16 v[80:95], v[0:3], v[128:131], v[80:95]
	v_cndmask_b32_e64 v0, 0, v185, s[8:9]
	v_cndmask_b32_e64 v64, v0, v184, s[6:7]
	v_mov_b32_e32 v65, v64
	v_mov_b64_e32 v[66:67], v[64:65]
	v_mov_b64_e32 v[68:69], v[64:65]
	v_mov_b64_e32 v[70:71], v[64:65]
	v_mov_b64_e32 v[72:73], v[64:65]
	v_mov_b64_e32 v[74:75], v[64:65]
	v_mov_b64_e32 v[76:77], v[64:65]
	v_mov_b64_e32 v[78:79], v[64:65]
	v_lshlrev_b32_e32 v1, 3, v20
	v_lshlrev_b32_e32 v0, 8, v21
	v_mfma_f32_32x32x16_bf16 v[64:79], v[4:7], v[140:143], v[64:79]
	v_and_b32_e32 v1, 8, v1
	v_bitop3_b32 v2, v22, v202, v23 bitop3:0x36
	v_lshlrev_b32_e32 v2, 4, v2
	v_or3_b32 v0, v1, v24, v0
	v_lshlrev_b32_e32 v3, 6, v21
	v_xor_b32_e32 v1, 32, v2
	v_or_b32_e32 v4, v0, v3
	v_mfma_f32_32x32x16_bf16 v[64:79], v[8:11], v[136:139], v[64:79]
	v_bitop3_b32 v6, v0, 64, v3 bitop3:0x36
	v_bitop3_b32 v8, v0, s38, v3 bitop3:0x36
	v_bitop3_b32 v0, v0, s39, v3 bitop3:0x36
	v_add_u32_e32 v5, v4, v2
	v_add_u32_e32 v4, v1, v4
	v_add_u32_e32 v7, v6, v2
	v_add_u32_e32 v6, v6, v1
	v_mfma_f32_32x32x16_bf16 v[64:79], v[12:15], v[132:135], v[64:79]
	v_add_u32_e32 v9, v8, v2
	v_add_u32_e32 v8, v8, v1
	v_add_u32_e32 v2, v0, v2
	v_add_u32_e32 v0, v0, v1
	v_add_u32_e32 v210, s70, v5
	v_add_u32_e32 v211, s70, v4
	v_add_u32_e32 v208, s70, v7
	v_mfma_f32_32x32x16_bf16 v[64:79], v[16:19], v[128:131], v[64:79]
	v_add_u32_e32 v209, s70, v6
	v_add_u32_e32 v206, s70, v9
	v_add_u32_e32 v207, s70, v8
	v_add_u32_e32 v204, s70, v2
	v_add_u32_e32 v205, s70, v0
	v_mov_b32_e32 v49, v213
	v_mov_b32_e32 v50, v213
	v_mov_b32_e32 v51, v213
	v_mov_b32_e32 v52, v213
	v_mov_b32_e32 v53, v213
	v_mov_b32_e32 v54, v213
	v_mov_b32_e32 v55, v213
	v_mov_b32_e32 v56, v213
	v_mov_b32_e32 v57, v213
	v_mov_b32_e32 v58, v213
	v_mov_b32_e32 v59, v213
	v_mov_b32_e32 v60, v213
	v_mov_b32_e32 v61, v213
	v_mov_b32_e32 v62, v213
	v_mov_b32_e32 v63, v213
	v_mov_b32_e32 v32, 0
	v_mov_b32_e32 v33, v213
	v_mov_b32_e32 v34, v213
	v_mov_b32_e32 v35, v213
	v_mov_b32_e32 v36, v213
	v_mov_b32_e32 v37, v213
	v_mov_b32_e32 v38, v213
	v_mov_b32_e32 v39, v213
	v_mov_b32_e32 v40, v213
	v_mov_b32_e32 v41, v213
	v_mov_b32_e32 v42, v213
	v_mov_b32_e32 v43, v213
	v_mov_b32_e32 v44, v213
	v_mov_b32_e32 v45, v213
	v_mov_b32_e32 v46, v213
	v_mov_b32_e32 v47, v213
	v_mov_b32_e32 v16, 0
	v_mov_b32_e32 v17, v213
	v_mov_b32_e32 v18, v213
	v_mov_b32_e32 v19, v213
	v_mov_b32_e32 v20, v213
	v_mov_b32_e32 v21, v213
	v_mov_b32_e32 v22, v213
	v_mov_b32_e32 v23, v213
	v_mov_b32_e32 v24, v213
	v_mov_b32_e32 v25, v213
	v_mov_b32_e32 v26, v213
	v_mov_b32_e32 v27, v213
	v_mov_b32_e32 v28, v213
	v_mov_b32_e32 v29, v213
	v_mov_b32_e32 v30, v213
	v_mov_b32_e32 v31, v213
	v_mov_b32_e32 v0, 0
	v_mov_b32_e32 v1, v213
	v_mov_b32_e32 v2, v213
	v_mov_b32_e32 v3, v213
	v_mov_b32_e32 v4, v213
	v_mov_b32_e32 v5, v213
	v_mov_b32_e32 v6, v213
	v_mov_b32_e32 v7, v213
	v_mov_b32_e32 v8, v213
	v_mov_b32_e32 v9, v213
	v_mov_b32_e32 v10, v213
	v_mov_b32_e32 v11, v213
	v_mov_b32_e32 v12, v213
	v_mov_b32_e32 v13, v213
	v_mov_b32_e32 v14, v213
	v_mov_b32_e32 v15, v213
.LBB0_641:
	ds_read_b128 v[172:175], v214 offset:32768
	ds_read_b128 v[156:159], v214 offset:40960
	ds_read_b128 v[168:171], v215 offset:32768
	ds_read_b128 v[152:155], v215 offset:40960
	ds_read_b128 v[164:167], v216 offset:32768
	ds_read_b128 v[148:151], v216 offset:40960
	ds_read_b128 v[160:163], v217 offset:32768
	ds_read_b128 v[144:147], v217 offset:40960
	s_add_i32 s57, s58, 0x80
	s_and_b32 s59, s57, 0x780
	s_mul_i32 s10, s59, 0x1c00
	s_add_u32 s10, s12, s10
	s_addc_u32 s11, s55, 0
	v_lshl_add_u64 v[194:195], s[10:11], 0, v[190:191]
	v_lshl_add_u64 v[196:197], s[10:11], 0, v[192:193]
	s_add_i32 s10, s58, 64
	s_and_b32 s60, s10, 0x7c0
	s_mul_i32 s10, s60, 0x1c00
	s_add_u32 s10, s12, s10
	s_mov_b32 m0, s41
	s_addc_u32 s11, s55, 0
	global_load_lds_dwordx4 v[194:195], off
	s_mov_b32 m0, s42
	v_lshl_add_u64 v[96:97], s[10:11], 0, v[190:191]
	global_load_lds_dwordx4 v[196:197], off
	v_lshl_add_u64 v[96:97], v[96:97], 0, s[26:27]
	s_mov_b32 m0, s47
	s_nop 0
	global_load_lds_dwordx4 v[96:97], off
	v_lshl_add_u64 v[96:97], s[10:11], 0, v[192:193]
	v_lshl_add_u64 v[96:97], v[96:97], 0, s[26:27]
	s_mov_b32 m0, s48
	s_and_b32 s10, s58, 0x780
	global_load_lds_dwordx4 v[96:97], off
	s_sub_i32 s11, s10, s53
	s_add_i32 s61, s11, 0xffffff86
	v_sub_u32_e32 v96, s11, v203
	s_cmp_gt_u32 s61, 0xffffff0c
	v_lshl_add_u32 v96, v96, 2, v212
	s_cbranch_scc0 .LBB0_643
	ds_read2_b32 v[98:99], v96 offset0:160 offset1:161
	ds_read2_b32 v[100:101], v96 offset0:162 offset1:163
	ds_read2_b32 v[102:103], v96 offset0:168 offset1:169
	ds_read2_b32 v[104:105], v96 offset0:170 offset1:171
	s_waitcnt lgkmcnt(0)
	v_pk_add_f32 v[80:81], v[80:81], v[98:99]
	v_pk_add_f32 v[82:83], v[82:83], v[100:101]
	v_pk_add_f32 v[84:85], v[84:85], v[102:103]
	ds_read2_b32 v[98:99], v96 offset0:176 offset1:177
	ds_read2_b32 v[100:101], v96 offset0:178 offset1:179
	ds_read2_b32 v[102:103], v96 offset0:184 offset1:185
	ds_read2_b32 v[106:107], v96 offset0:186 offset1:187
	v_pk_add_f32 v[86:87], v[86:87], v[104:105]
	s_waitcnt lgkmcnt(0)
	v_pk_add_f32 v[88:89], v[88:89], v[98:99]
	v_pk_add_f32 v[90:91], v[90:91], v[100:101]
	v_pk_add_f32 v[92:93], v[92:93], v[102:103]
	v_pk_add_f32 v[94:95], v[94:95], v[106:107]

.LBB0_645:
	s_sub_i32 s61, s60, s53
	s_or_b32 s10, s61, 31
	s_cmpk_lt_i32 s10, 0xffa6
	s_cselect_b64 vcc, -1, 0
	s_cmpk_gt_i32 s61, 0x79
	s_cselect_b64 s[10:11], -1, 0
	v_cndmask_b32_e64 v96, 0, v185, s[10:11]
	s_or_b32 s10, s60, 32
	s_sub_i32 s60, s10, s53
	s_or_b32 s10, s60, 31
	s_cmpk_lt_i32 s10, 0xffa6
	v_cndmask_b32_e32 v112, v96, v184, vcc
	s_cselect_b64 vcc, -1, 0
	s_cmpk_gt_i32 s60, 0x79
	s_cselect_b64 s[10:11], -1, 0
	v_cndmask_b32_e64 v96, 0, v185, s[10:11]
	v_cndmask_b32_e32 v96, v96, v184, vcc
	v_mov_b32_e32 v113, v112
	v_mov_b64_e32 v[114:115], v[112:113]
	v_mov_b64_e32 v[116:117], v[112:113]
	v_mov_b64_e32 v[118:119], v[112:113]
	v_mov_b64_e32 v[120:121], v[112:113]
	v_mov_b64_e32 v[122:123], v[112:113]
	v_mov_b64_e32 v[124:125], v[112:113]
	v_mov_b64_e32 v[126:127], v[112:113]
	v_mov_b32_e32 v97, v96
	v_mov_b64_e32 v[98:99], v[96:97]
	v_mov_b64_e32 v[100:101], v[96:97]
	v_mov_b64_e32 v[102:103], v[96:97]
	v_mov_b64_e32 v[104:105], v[96:97]
	v_mov_b64_e32 v[106:107], v[96:97]
	v_mov_b64_e32 v[108:109], v[96:97]
	v_mov_b64_e32 v[110:111], v[96:97]
	s_waitcnt lgkmcnt(0)
	v_mfma_f32_32x32x16_bf16 v[112:127], v[172:175], v[140:143], v[112:127]
	ds_read_b64_tr_b16 v[218:219], v210 offset:16384
	ds_read_b64_tr_b16 v[220:221], v211 offset:18432
	v_exp_f32_e32 v80, v80
	v_exp_f32_e32 v81, v81
	v_mfma_f32_32x32x16_bf16 v[112:127], v[168:171], v[136:139], v[112:127]
	ds_read_b64_tr_b16 v[172:173], v208 offset:16384
	ds_read_b64_tr_b16 v[174:175], v209 offset:18432
	v_exp_f32_e32 v82, v82
	v_exp_f32_e32 v83, v83
	v_mfma_f32_32x32x16_bf16 v[112:127], v[164:167], v[132:135], v[112:127]
	ds_read_b64_tr_b16 v[168:169], v206 offset:16384
	ds_read_b64_tr_b16 v[170:171], v207 offset:18432
	v_exp_f32_e32 v84, v84
	v_exp_f32_e32 v85, v85
	v_mfma_f32_32x32x16_bf16 v[112:127], v[160:163], v[128:131], v[112:127]
	ds_read_b64_tr_b16 v[222:223], v204 offset:16384
	ds_read_b64_tr_b16 v[224:225], v205 offset:18432
	v_exp_f32_e32 v86, v86
	v_exp_f32_e32 v87, v87
	v_mfma_f32_32x32x16_bf16 v[96:111], v[156:159], v[140:143], v[96:111]
	ds_read_b64_tr_b16 v[160:161], v210 offset:20480
	ds_read_b64_tr_b16 v[162:163], v211 offset:22528
	v_exp_f32_e32 v88, v88
	v_exp_f32_e32 v89, v89
	v_mfma_f32_32x32x16_bf16 v[96:111], v[152:155], v[136:139], v[96:111]
	ds_read_b64_tr_b16 v[156:157], v208 offset:20480
	ds_read_b64_tr_b16 v[158:159], v209 offset:22528
	v_exp_f32_e32 v90, v90
	v_exp_f32_e32 v91, v91
	v_mfma_f32_32x32x16_bf16 v[96:111], v[148:151], v[132:135], v[96:111]
	ds_read_b64_tr_b16 v[152:153], v206 offset:20480
	ds_read_b64_tr_b16 v[154:155], v207 offset:22528
	v_exp_f32_e32 v92, v92
	v_exp_f32_e32 v93, v93
	v_mfma_f32_32x32x16_bf16 v[96:111], v[144:147], v[128:131], v[96:111]
	ds_read_b64_tr_b16 v[148:149], v204 offset:20480
	ds_read_b64_tr_b16 v[150:151], v205 offset:22528
	v_exp_f32_e32 v94, v94
	v_exp_f32_e32 v95, v95
	v_cvt_pk_bf16_f32 v144, v80, v81
	v_cvt_pk_bf16_f32 v145, v82, v83
	v_cvt_pk_bf16_f32 v146, v84, v85
	v_cvt_pk_bf16_f32 v147, v86, v87
	v_cvt_pk_bf16_f32 v226, v88, v89
	v_cvt_pk_bf16_f32 v227, v90, v91
	v_cvt_pk_bf16_f32 v228, v92, v93
	v_cvt_pk_bf16_f32 v229, v94, v95
	s_waitcnt lgkmcnt(14)
	v_mfma_f32_32x32x16_bf16 v[48:63], v[218:221], v[144:147], v[48:63]
	ds_read_b64_tr_b16 v[230:231], v210 offset:24576
	ds_read_b64_tr_b16 v[232:233], v211 offset:26624
	v_exp_f32_e32 v64, v64
	v_exp_f32_e32 v65, v65
	s_waitcnt lgkmcnt(14)
	v_mfma_f32_32x32x16_bf16 v[32:47], v[172:175], v[144:147], v[32:47]
	ds_read_b64_tr_b16 v[218:219], v208 offset:24576
	ds_read_b64_tr_b16 v[220:221], v209 offset:26624
	v_exp_f32_e32 v164, v66
	v_exp_f32_e32 v165, v67
	s_waitcnt lgkmcnt(14)
	v_mfma_f32_32x32x16_bf16 v[16:31], v[168:171], v[144:147], v[16:31]
	v_exp_f32_e32 v166, v68
	v_exp_f32_e32 v167, v69
	ds_read_b64_tr_b16 v[66:67], v206 offset:24576
	ds_read_b64_tr_b16 v[68:69], v207 offset:26624
	s_waitcnt lgkmcnt(14)
	v_mfma_f32_32x32x16_bf16 v[0:15], v[222:225], v[144:147], v[0:15]
	ds_read_b64_tr_b16 v[234:235], v204 offset:24576
	ds_read_b64_tr_b16 v[236:237], v205 offset:26624
	v_exp_f32_e32 v168, v70
	v_exp_f32_e32 v169, v71
	s_waitcnt lgkmcnt(14)
	v_mfma_f32_32x32x16_bf16 v[48:63], v[160:163], v[226:229], v[48:63]
	v_exp_f32_e32 v170, v72
	v_exp_f32_e32 v171, v73
	ds_read_b64_tr_b16 v[70:71], v210 offset:28672
	ds_read_b64_tr_b16 v[72:73], v211 offset:30720
	s_waitcnt lgkmcnt(14)
	v_mfma_f32_32x32x16_bf16 v[32:47], v[156:159], v[226:229], v[32:47]
	ds_read_b64_tr_b16 v[144:145], v208 offset:28672
	ds_read_b64_tr_b16 v[146:147], v209 offset:30720
	v_exp_f32_e32 v172, v74
	v_exp_f32_e32 v173, v75
	s_waitcnt lgkmcnt(14)
	v_mfma_f32_32x32x16_bf16 v[16:31], v[152:155], v[226:229], v[16:31]
	v_exp_f32_e32 v174, v76
	v_exp_f32_e32 v175, v77
	ds_read_b64_tr_b16 v[74:75], v206 offset:28672
	ds_read_b64_tr_b16 v[76:77], v207 offset:30720
	s_waitcnt lgkmcnt(14)
	v_mfma_f32_32x32x16_bf16 v[0:15], v[148:151], v[226:229], v[0:15]
	ds_read_b64_tr_b16 v[152:153], v204 offset:28672
	ds_read_b64_tr_b16 v[154:155], v205 offset:30720
	v_exp_f32_e32 v78, v78
	v_exp_f32_e32 v79, v79
	v_cvt_pk_bf16_f32 v148, v64, v65
	v_cvt_pk_bf16_f32 v149, v164, v165
	v_cvt_pk_bf16_f32 v150, v166, v167
	v_cvt_pk_bf16_f32 v151, v168, v169
	v_cvt_pk_bf16_f32 v156, v170, v171
	v_cvt_pk_bf16_f32 v157, v172, v173
	v_cvt_pk_bf16_f32 v158, v174, v175
	v_cvt_pk_bf16_f32 v159, v78, v79
	s_waitcnt lgkmcnt(14)
	v_mfma_f32_32x32x16_bf16 v[48:63], v[230:233], v[148:151], v[48:63]
	s_waitcnt lgkmcnt(12)
	v_mfma_f32_32x32x16_bf16 v[32:47], v[218:221], v[148:151], v[32:47]
	s_waitcnt lgkmcnt(10)
	v_mfma_f32_32x32x16_bf16 v[16:31], v[66:69], v[148:151], v[16:31]
	s_waitcnt lgkmcnt(8)
	v_mfma_f32_32x32x16_bf16 v[0:15], v[234:237], v[148:151], v[0:15]
	s_waitcnt lgkmcnt(6)
	v_mfma_f32_32x32x16_bf16 v[48:63], v[70:73], v[156:159], v[48:63]
	s_waitcnt lgkmcnt(4)
	v_mfma_f32_32x32x16_bf16 v[32:47], v[144:147], v[156:159], v[32:47]
	s_waitcnt lgkmcnt(2)
	v_mfma_f32_32x32x16_bf16 v[16:31], v[74:77], v[156:159], v[16:31]
	s_waitcnt lgkmcnt(0)
	v_mfma_f32_32x32x16_bf16 v[0:15], v[152:155], v[156:159], v[0:15]
	s_add_i32 s10, s58, 0xc0
	s_and_b32 s10, s10, 0x7c0
	s_mulk_i32 s10, 0x1c00
	s_add_u32 s10, s12, s10
	s_addc_u32 s11, s55, 0
	s_mov_b32 m0, s45
	s_waitcnt vmcnt(0) lgkmcnt(0)
	s_barrier
	ds_read_b128 v[160:163], v214
	ds_read_b128 v[156:159], v214 offset:8192
	ds_read_b128 v[74:77], v215
	ds_read_b128 v[152:155], v215 offset:8192
	ds_read_b128 v[70:73], v216
	ds_read_b128 v[148:151], v216 offset:8192
	ds_read_b128 v[144:147], v217 offset:8192
	v_lshl_add_u64 v[66:67], v[186:187], 1, s[10:11]
	global_load_lds_dwordx4 v[66:67], off
	v_lshl_add_u64 v[66:67], v[188:189], 1, s[10:11]
	s_mov_b32 m0, s46
	s_add_i32 s10, s61, 0xffffff86
	global_load_lds_dwordx4 v[66:67], off
	v_lshl_add_u64 v[66:67], v[194:195], 0, s[26:27]
	s_mov_b32 m0, s43
	v_sub_u32_e32 v194, s61, v203
	global_load_lds_dwordx4 v[66:67], off
	v_lshl_add_u64 v[66:67], v[196:197], 0, s[26:27]
	s_mov_b32 m0, s44
	s_cmp_lt_u32 s10, 0xffffff0d
	global_load_lds_dwordx4 v[66:67], off
	ds_read_b128 v[66:69], v217
	v_lshl_add_u32 v194, v194, 2, v212
	s_cbranch_scc1 .LBB0_647
	ds_read2_b32 v[196:197], v194 offset0:176 offset1:177
	ds_read2_b32 v[218:219], v194 offset0:178 offset1:179
	ds_read2_b32 v[220:221], v194 offset0:184 offset1:185
	ds_read2_b32 v[222:223], v194 offset0:186 offset1:187
	ds_read2_b32 v[224:225], v194 offset0:160 offset1:161
	ds_read2_b32 v[226:227], v194 offset0:162 offset1:163
	ds_read2_b32 v[228:229], v194 offset0:168 offset1:169
	ds_read2_b32 v[230:231], v194 offset0:170 offset1:171
	s_waitcnt lgkmcnt(0)
	v_pk_add_f32 v[126:127], v[126:127], v[222:223]
	v_pk_add_f32 v[124:125], v[124:125], v[220:221]
	v_pk_add_f32 v[122:123], v[122:123], v[218:219]
	v_pk_add_f32 v[120:121], v[120:121], v[196:197]
	v_pk_add_f32 v[118:119], v[118:119], v[230:231]
	v_pk_add_f32 v[116:117], v[116:117], v[228:229]
	v_pk_add_f32 v[114:115], v[114:115], v[226:227]
	v_pk_add_f32 v[112:113], v[112:113], v[224:225]

.LBB0_649:
	v_add_f32_e32 v80, v80, v81
	v_add_f32_e32 v80, v213, v80
	v_add_f32_e32 v81, v82, v83
	v_add_f32_e32 v80, v81, v80
	v_add_f32_e32 v81, v84, v85
	v_add_f32_e32 v80, v81, v80
	v_add_f32_e32 v81, v86, v87
	v_add_f32_e32 v80, v81, v80
	v_add_f32_e32 v81, v88, v89
	v_add_f32_e32 v80, v81, v80
	v_add_f32_e32 v81, v90, v91
	v_add_f32_e32 v80, v81, v80
	v_add_f32_e32 v81, v92, v93
	v_add_f32_e32 v80, v81, v80
	v_add_f32_e32 v81, v94, v95
	v_add_f32_e32 v80, v81, v80
	v_add_f32_e32 v64, v64, v65
	v_add_f32_e32 v65, v164, v165
	v_add_f32_e32 v64, v64, v80
	v_add_f32_e32 v81, v166, v167
	v_add_f32_e32 v64, v65, v64
	s_sub_i32 s10, s59, s53
	v_add_f32_e32 v82, v168, v169
	v_add_f32_e32 v64, v81, v64
	s_or_b32 s11, s10, 31
	v_add_f32_e32 v83, v170, v171
	v_add_f32_e32 v64, v82, v64
	s_cmpk_lt_i32 s11, 0xffa6
	v_add_f32_e32 v84, v172, v173
	v_add_f32_e32 v64, v83, v64
	s_cselect_b64 vcc, -1, 0
	s_cmpk_gt_i32 s10, 0x79
	v_add_f32_e32 v85, v174, v175
	v_add_f32_e32 v64, v84, v64
	s_cselect_b64 s[10:11], -1, 0
	v_add_f32_e32 v218, v85, v64
	v_cndmask_b32_e64 v64, 0, v185, s[10:11]
	s_or_b32 s10, s59, 32
	s_sub_i32 s10, s10, s53
	s_or_b32 s11, s10, 31
	s_cmpk_lt_i32 s11, 0xffa6
	v_cndmask_b32_e32 v80, v64, v184, vcc
	s_cselect_b64 vcc, -1, 0
	s_cmpk_gt_i32 s10, 0x79
	s_cselect_b64 s[10:11], -1, 0
	v_cndmask_b32_e64 v64, 0, v185, s[10:11]
	v_add_f32_e32 v213, v78, v79
	v_cndmask_b32_e32 v64, v64, v184, vcc
	v_mov_b32_e32 v81, v80
	v_mov_b64_e32 v[82:83], v[80:81]
	v_mov_b64_e32 v[84:85], v[80:81]
	v_mov_b64_e32 v[86:87], v[80:81]
	v_mov_b64_e32 v[88:89], v[80:81]
	v_mov_b64_e32 v[90:91], v[80:81]
	v_mov_b64_e32 v[92:93], v[80:81]
	v_mov_b64_e32 v[94:95], v[80:81]
	ds_read_b64_tr_b16 v[164:165], v210 offset:49152
	ds_read_b64_tr_b16 v[166:167], v211 offset:51200
	s_waitcnt lgkmcnt(0)
	v_mfma_f32_32x32x16_bf16 v[80:95], v[160:163], v[140:143], v[80:95]
	v_exp_f32_e32 v220, v112
	v_exp_f32_e32 v222, v113
	v_mfma_f32_32x32x16_bf16 v[80:95], v[74:77], v[136:139], v[80:95]
	v_exp_f32_e32 v223, v114
	v_exp_f32_e32 v224, v115
	ds_read_b64_tr_b16 v[112:113], v208 offset:49152
	ds_read_b64_tr_b16 v[114:115], v209 offset:51200
	v_mfma_f32_32x32x16_bf16 v[80:95], v[70:73], v[132:135], v[80:95]
	ds_read_b64_tr_b16 v[160:161], v206 offset:49152
	ds_read_b64_tr_b16 v[162:163], v207 offset:51200
	v_exp_f32_e32 v225, v116
	v_exp_f32_e32 v226, v117
	v_mfma_f32_32x32x16_bf16 v[80:95], v[66:69], v[128:131], v[80:95]
	v_exp_f32_e32 v227, v118
	v_exp_f32_e32 v228, v119
	ds_read_b64_tr_b16 v[116:117], v204 offset:49152
	ds_read_b64_tr_b16 v[118:119], v205 offset:51200
	v_mov_b32_e32 v65, v64
	v_mov_b64_e32 v[66:67], v[64:65]
	v_mov_b64_e32 v[68:69], v[64:65]
	v_mov_b64_e32 v[70:71], v[64:65]
	v_mov_b64_e32 v[72:73], v[64:65]
	v_mov_b64_e32 v[74:75], v[64:65]
	v_mov_b64_e32 v[76:77], v[64:65]
	v_mov_b64_e32 v[78:79], v[64:65]
	ds_read_b64_tr_b16 v[168:169], v210 offset:53248
	ds_read_b64_tr_b16 v[170:171], v211 offset:55296
	v_mfma_f32_32x32x16_bf16 v[64:79], v[156:159], v[140:143], v[64:79]
	v_exp_f32_e32 v173, v120
	v_exp_f32_e32 v175, v121
	v_mfma_f32_32x32x16_bf16 v[64:79], v[152:155], v[136:139], v[64:79]
	v_exp_f32_e32 v172, v122
	v_exp_f32_e32 v174, v123
	ds_read_b64_tr_b16 v[120:121], v208 offset:53248
	ds_read_b64_tr_b16 v[122:123], v209 offset:55296
	v_mfma_f32_32x32x16_bf16 v[64:79], v[148:151], v[132:135], v[64:79]
	ds_read_b64_tr_b16 v[152:153], v206 offset:53248
	ds_read_b64_tr_b16 v[154:155], v207 offset:55296
	v_exp_f32_e32 v195, v124
	v_exp_f32_e32 v197, v125
	v_mfma_f32_32x32x16_bf16 v[64:79], v[144:147], v[128:131], v[64:79]
	v_exp_f32_e32 v194, v126
	v_exp_f32_e32 v196, v127
	ds_read_b64_tr_b16 v[124:125], v204 offset:53248
	ds_read_b64_tr_b16 v[126:127], v205 offset:55296
	v_add_f32_e32 v148, v213, v218
	v_cvt_pk_bf16_f32 v144, v220, v222
	v_cvt_pk_bf16_f32 v145, v223, v224
	v_cvt_pk_bf16_f32 v146, v225, v226
	v_cvt_pk_bf16_f32 v147, v227, v228
	s_nop 1
	v_mfma_f32_32x32x16_bf16 v[48:63], v[164:167], v[144:147], v[48:63]
	v_exp_f32_e32 v219, v96
	v_add_f32_e32 v96, v220, v222
	v_add_f32_e32 v96, v148, v96
	ds_read_b64_tr_b16 v[148:149], v210 offset:57344
	ds_read_b64_tr_b16 v[150:151], v211 offset:59392
	v_exp_f32_e32 v221, v97
	s_waitcnt lgkmcnt(14)
	v_mfma_f32_32x32x16_bf16 v[32:47], v[112:115], v[144:147], v[32:47]
	v_add_f32_e32 v97, v223, v224
	v_exp_f32_e32 v218, v98
	v_exp_f32_e32 v220, v99
	v_add_f32_e32 v156, v97, v96
	ds_read_b64_tr_b16 v[96:97], v208 offset:57344
	ds_read_b64_tr_b16 v[98:99], v209 offset:59392
	s_waitcnt lgkmcnt(14)
	v_mfma_f32_32x32x16_bf16 v[16:31], v[160:163], v[144:147], v[16:31]
	ds_read_b64_tr_b16 v[112:113], v206 offset:57344
	ds_read_b64_tr_b16 v[114:115], v207 offset:59392
	v_exp_f32_e32 v165, v100
	v_add_f32_e32 v100, v225, v226
	v_exp_f32_e32 v167, v101
	v_add_f32_e32 v100, v100, v156
	s_waitcnt lgkmcnt(14)
; #define DA_DMAK(kt, slot) do { _Pragma("unroll") for (int i_ = 0; i_ < 2; ++i_) __builtin_amdgcn_global_load_lds((const unsigned*)(kbase + (size_t)((((kt) + rot) & 31) * 64) * NIN + dsrc[i_]), \
;         (LAS unsigned*)(lds + (slot) * 32768 + (2 * wid + i_) * 1024), 16, 0, 0); } while (0)
; #define DA_DMAV(kt, slot) do { _Pragma("unroll") for (int i_ = 0; i_ < 2; ++i_) __builtin_amdgcn_global_load_lds((const unsigned*)(kbase + 512 + (size_t)((((kt) + rot) & 31) * 64) * NIN + dsrc[i_]), \
;         (LAS unsigned*)(lds + (slot) * 32768 + 16384 + (2 * wid + i_) * 1024), 16, 0, 0); } while (0)
; #define DA_WAITBAR() asm volatile("s_waitcnt vmcnt(0) lgkmcnt(0)\n\ts_barrier" ::: "memory")
; __device__ __forceinline__ void dattn_unit(const Args& a, unsigned char* ws, LAS unsigned char* lds, int l, int unit, int tid, int wid, int lane, int dry) {
;     ...
;     f32x16 SA[2], SB[2];
;     DA_DMAK(0, 0); DA_DMAV(0, 0); DA_DMAK(1, 1);
;     DA_WAITBAR();
;     DA_QK(0, 0, SA);
;     DA_WAITBAR();
;     for (int kt = 0; kt < 30; kt += 2) { DA_STEP(kt, 0, SA, SB, true, true, true); DA_STEP(kt + 1, 1, SB, SA, true, true, true); }
;     DA_STEP(30, 0, SA, SB, false, true, true);
	v_mfma_f32_32x32x16_bf16 v[0:15], v[116:119], v[144:147], v[0:15]
	v_add_f32_e32 v101, v227, v228
	v_exp_f32_e32 v164, v102
	v_exp_f32_e32 v166, v103
	v_add_f32_e32 v156, v101, v100
	ds_read_b64_tr_b16 v[100:101], v204 offset:57344
	ds_read_b64_tr_b16 v[102:103], v205 offset:59392
	ds_read_b64_tr_b16 v[116:117], v210 offset:61440
	ds_read_b64_tr_b16 v[118:119], v211 offset:63488
	v_exp_f32_e32 v161, v104
	v_exp_f32_e32 v163, v105
	ds_read_b64_tr_b16 v[144:145], v208 offset:61440
	ds_read_b64_tr_b16 v[146:147], v209 offset:63488
	v_exp_f32_e32 v160, v106
	v_exp_f32_e32 v162, v107
	v_pk_add_f32 v[106:107], v[172:173], v[174:175]
	v_cvt_pk_bf16_f32 v104, v173, v175
	v_add_f32_e32 v107, v107, v156
	v_add_f32_e32 v213, v106, v107
	v_cvt_pk_bf16_f32 v105, v172, v174
	ds_read_b64_tr_b16 v[156:157], v206 offset:61440
	ds_read_b64_tr_b16 v[158:159], v207 offset:63488
	v_exp_f32_e32 v173, v108
	v_exp_f32_e32 v175, v109
	v_cvt_pk_bf16_f32 v106, v195, v197
	v_cvt_pk_bf16_f32 v107, v194, v196
	v_pk_add_f32 v[108:109], v[194:195], v[196:197]
	v_exp_f32_e32 v172, v110
	s_waitcnt lgkmcnt(14)
	v_mfma_f32_32x32x16_bf16 v[48:63], v[168:171], v[104:107], v[48:63]
	v_add_f32_e32 v109, v109, v213
	v_exp_f32_e32 v174, v111
	v_mfma_f32_32x32x16_bf16 v[32:47], v[120:123], v[104:107], v[32:47]
	v_add_f32_e32 v120, v108, v109
	ds_read_b64_tr_b16 v[108:109], v204 offset:61440
	ds_read_b64_tr_b16 v[110:111], v205 offset:63488
	v_mfma_f32_32x32x16_bf16 v[16:31], v[152:155], v[104:107], v[16:31]
	v_mfma_f32_32x32x16_bf16 v[0:15], v[124:127], v[104:107], v[0:15]
	v_add_f32_e64 v106, v218, v220
	v_add_f32_e64 v107, v219, v221
	v_cvt_pk_bf16_f32 v104, v219, v221
	v_add_f32_e32 v107, v120, v107
	v_cvt_pk_bf16_f32 v105, v218, v220
	v_add_f32_e32 v120, v106, v107
	v_cvt_pk_bf16_f32 v106, v165, v167
	v_cvt_pk_bf16_f32 v107, v164, v166
	s_waitcnt lgkmcnt(14)
	s_nop 0
	v_mfma_f32_32x32x16_bf16 v[48:63], v[148:151], v[104:107], v[48:63]
	s_waitcnt lgkmcnt(12)
	v_mfma_f32_32x32x16_bf16 v[32:47], v[96:99], v[104:107], v[32:47]
	v_add_f32_e64 v96, v164, v166
	v_add_f32_e64 v97, v165, v167
	v_add_f32_e32 v97, v97, v120
	s_waitcnt lgkmcnt(10)
	v_mfma_f32_32x32x16_bf16 v[16:31], v[112:115], v[104:107], v[16:31]
	v_add_f32_e32 v112, v96, v97
	s_waitcnt lgkmcnt(8)
	v_mfma_f32_32x32x16_bf16 v[0:15], v[100:103], v[104:107], v[0:15]
	v_add_f32_e64 v98, v160, v162
	v_add_f32_e64 v99, v161, v163
	v_cvt_pk_bf16_f32 v96, v161, v163
	v_add_f32_e32 v99, v99, v112
	v_cvt_pk_bf16_f32 v97, v160, v162
	v_add_f32_e32 v102, v98, v99
	v_cvt_pk_bf16_f32 v98, v173, v175
	v_cvt_pk_bf16_f32 v99, v172, v174
	v_pk_add_f32 v[100:101], v[172:173], v[174:175]
	s_waitcnt lgkmcnt(6)
	v_mfma_f32_32x32x16_bf16 v[48:63], v[116:119], v[96:99], v[48:63]
	v_add_f32_e32 v101, v101, v102
	v_add_f32_e32 v213, v100, v101
	s_waitcnt lgkmcnt(4)
	v_mfma_f32_32x32x16_bf16 v[32:47], v[144:147], v[96:99], v[32:47]
	s_waitcnt lgkmcnt(2)
	v_mfma_f32_32x32x16_bf16 v[16:31], v[156:159], v[96:99], v[16:31]
	s_waitcnt lgkmcnt(0)
	v_mfma_f32_32x32x16_bf16 v[0:15], v[108:111], v[96:99], v[0:15]
	s_waitcnt vmcnt(0) lgkmcnt(0)
	s_barrier
	s_add_i32 s56, s56, 2
	s_cmp_gt_u32 s56, 27
	s_cbranch_scc1 .LBB0_651
	s_mov_b32 s58, s57
	s_branch .LBB0_641
.LBB0_651:
	ds_read_b128 v[172:175], v214 offset:32768
	ds_read_b128 v[156:159], v214 offset:40960
	ds_read_b128 v[168:171], v215 offset:32768
	ds_read_b128 v[152:155], v215 offset:40960
	ds_read_b128 v[164:167], v216 offset:32768
	ds_read_b128 v[148:151], v216 offset:40960
	ds_read_b128 v[160:163], v217 offset:32768
	ds_read_b128 v[144:147], v217 offset:40960
	s_add_i32 s10, s54, 0x7c0
	s_and_b32 s56, s10, 0x7c0
	s_mul_i32 s10, s56, 0x1c00
	s_add_u32 s10, s12, s10
	s_addc_u32 s11, s55, 0
	v_lshl_add_u64 v[96:97], v[186:187], 1, s[10:11]
	s_mov_b32 m0, s47
	v_lshl_add_u64 v[96:97], v[96:97], 0, s[26:27]
	global_load_lds_dwordx4 v[96:97], off
	v_lshl_add_u64 v[96:97], v[188:189], 1, s[10:11]
	v_lshl_add_u64 v[96:97], v[96:97], 0, s[26:27]
	s_mov_b32 m0, s48
	s_addk_i32 s54, 0x780
	global_load_lds_dwordx4 v[96:97], off
	s_and_b32 s10, s54, 0x780
	s_sub_i32 s11, s10, s53
	s_add_i32 s12, s11, 0xffffff86
	v_sub_u32_e32 v96, s11, v203
	s_cmp_gt_u32 s12, 0xffffff0c
	v_lshl_add_u32 v96, v96, 2, v212
	s_cbranch_scc0 .LBB0_653
	ds_read2_b32 v[98:99], v96 offset0:160 offset1:161
	ds_read2_b32 v[100:101], v96 offset0:162 offset1:163
	ds_read2_b32 v[102:103], v96 offset0:168 offset1:169
	ds_read2_b32 v[104:105], v96 offset0:170 offset1:171
	s_waitcnt lgkmcnt(0)
	v_pk_add_f32 v[80:81], v[80:81], v[98:99]
	v_pk_add_f32 v[82:83], v[82:83], v[100:101]
	v_pk_add_f32 v[84:85], v[84:85], v[102:103]
	ds_read2_b32 v[98:99], v96 offset0:176 offset1:177
	ds_read2_b32 v[100:101], v96 offset0:178 offset1:179
	ds_read2_b32 v[102:103], v96 offset0:184 offset1:185
	ds_read2_b32 v[106:107], v96 offset0:186 offset1:187
	v_pk_add_f32 v[86:87], v[86:87], v[104:105]
	s_waitcnt lgkmcnt(0)
	v_pk_add_f32 v[88:89], v[88:89], v[98:99]
	v_pk_add_f32 v[90:91], v[90:91], v[100:101]
	v_pk_add_f32 v[92:93], v[92:93], v[102:103]
	v_pk_add_f32 v[94:95], v[94:95], v[106:107]

.LBB0_655:
	s_sub_i32 s54, s56, s53
	s_or_b32 s10, s54, 31
	s_cmpk_lt_i32 s10, 0xffa6
	s_cselect_b64 vcc, -1, 0
	s_cmpk_gt_i32 s54, 0x79
	s_cselect_b64 s[10:11], -1, 0
	v_cndmask_b32_e64 v96, 0, v185, s[10:11]
	s_or_b32 s10, s56, 32
	s_sub_i32 s12, s10, s53
	s_or_b32 s10, s12, 31
	s_cmpk_lt_i32 s10, 0xffa6
	v_cndmask_b32_e32 v112, v96, v184, vcc
	s_cselect_b64 vcc, -1, 0
	s_cmpk_gt_i32 s12, 0x79
	s_cselect_b64 s[10:11], -1, 0
	v_cndmask_b32_e64 v96, 0, v185, s[10:11]
	v_cndmask_b32_e32 v96, v96, v184, vcc
	v_mov_b32_e32 v113, v112
	v_mov_b64_e32 v[114:115], v[112:113]
	v_mov_b64_e32 v[116:117], v[112:113]
	v_mov_b64_e32 v[118:119], v[112:113]
	v_mov_b64_e32 v[120:121], v[112:113]
	v_mov_b64_e32 v[122:123], v[112:113]
	v_mov_b64_e32 v[124:125], v[112:113]
	v_mov_b64_e32 v[126:127], v[112:113]
	v_mov_b32_e32 v97, v96
	v_mov_b64_e32 v[98:99], v[96:97]
	v_mov_b64_e32 v[100:101], v[96:97]
	v_mov_b64_e32 v[102:103], v[96:97]
	v_mov_b64_e32 v[104:105], v[96:97]
	v_mov_b64_e32 v[106:107], v[96:97]
	v_mov_b64_e32 v[108:109], v[96:97]
	v_mov_b64_e32 v[110:111], v[96:97]
	s_waitcnt lgkmcnt(0)
	v_mfma_f32_32x32x16_bf16 v[112:127], v[172:175], v[140:143], v[112:127]
	ds_read_b64_tr_b16 v[184:185], v210 offset:16384
	ds_read_b64_tr_b16 v[186:187], v211 offset:18432
	v_exp_f32_e32 v80, v80
	v_exp_f32_e32 v81, v81
	v_mfma_f32_32x32x16_bf16 v[112:127], v[168:171], v[136:139], v[112:127]
	ds_read_b64_tr_b16 v[172:173], v208 offset:16384
	ds_read_b64_tr_b16 v[174:175], v209 offset:18432
	v_exp_f32_e32 v82, v82
	v_exp_f32_e32 v83, v83
	v_mfma_f32_32x32x16_bf16 v[112:127], v[164:167], v[132:135], v[112:127]
	ds_read_b64_tr_b16 v[168:169], v206 offset:16384
	ds_read_b64_tr_b16 v[170:171], v207 offset:18432
	v_exp_f32_e32 v84, v84
	v_exp_f32_e32 v85, v85
	v_mfma_f32_32x32x16_bf16 v[112:127], v[160:163], v[128:131], v[112:127]
	ds_read_b64_tr_b16 v[164:165], v204 offset:16384
	ds_read_b64_tr_b16 v[166:167], v205 offset:18432
	v_exp_f32_e32 v86, v86
	v_exp_f32_e32 v87, v87
	v_mfma_f32_32x32x16_bf16 v[96:111], v[156:159], v[140:143], v[96:111]
	ds_read_b64_tr_b16 v[160:161], v210 offset:20480
	ds_read_b64_tr_b16 v[162:163], v211 offset:22528
	v_exp_f32_e32 v88, v88
	v_exp_f32_e32 v89, v89
	v_mfma_f32_32x32x16_bf16 v[96:111], v[152:155], v[136:139], v[96:111]
	ds_read_b64_tr_b16 v[140:141], v208 offset:20480
	ds_read_b64_tr_b16 v[142:143], v209 offset:22528
	v_exp_f32_e32 v90, v90
	v_exp_f32_e32 v91, v91
	v_mfma_f32_32x32x16_bf16 v[96:111], v[148:151], v[132:135], v[96:111]
	ds_read_b64_tr_b16 v[136:137], v206 offset:20480
	ds_read_b64_tr_b16 v[138:139], v207 offset:22528
	v_exp_f32_e32 v92, v92
	v_exp_f32_e32 v93, v93
	v_mfma_f32_32x32x16_bf16 v[96:111], v[144:147], v[128:131], v[96:111]
	ds_read_b64_tr_b16 v[132:133], v204 offset:20480
	ds_read_b64_tr_b16 v[134:135], v205 offset:22528
	v_exp_f32_e32 v94, v94
	v_exp_f32_e32 v95, v95
	v_cvt_pk_bf16_f32 v128, v80, v81
	v_cvt_pk_bf16_f32 v129, v82, v83
	v_cvt_pk_bf16_f32 v130, v84, v85
	v_cvt_pk_bf16_f32 v131, v86, v87
	v_cvt_pk_bf16_f32 v144, v88, v89
	v_cvt_pk_bf16_f32 v145, v90, v91
	v_cvt_pk_bf16_f32 v146, v92, v93
	v_cvt_pk_bf16_f32 v147, v94, v95
	s_waitcnt lgkmcnt(14)
	v_mfma_f32_32x32x16_bf16 v[48:63], v[184:187], v[128:131], v[48:63]
	ds_read_b64_tr_b16 v[148:149], v210 offset:24576
	ds_read_b64_tr_b16 v[150:151], v211 offset:26624
	v_exp_f32_e32 v64, v64
	v_exp_f32_e32 v65, v65
	s_waitcnt lgkmcnt(14)
	v_mfma_f32_32x32x16_bf16 v[32:47], v[172:175], v[128:131], v[32:47]
	ds_read_b64_tr_b16 v[152:153], v208 offset:24576
	ds_read_b64_tr_b16 v[154:155], v209 offset:26624
	v_exp_f32_e32 v66, v66
	v_exp_f32_e32 v67, v67
	s_waitcnt lgkmcnt(14)
	v_mfma_f32_32x32x16_bf16 v[16:31], v[168:171], v[128:131], v[16:31]
	ds_read_b64_tr_b16 v[156:157], v206 offset:24576
	ds_read_b64_tr_b16 v[158:159], v207 offset:26624
	v_exp_f32_e32 v68, v68
	v_exp_f32_e32 v69, v69
	s_waitcnt lgkmcnt(14)
	v_mfma_f32_32x32x16_bf16 v[0:15], v[164:167], v[128:131], v[0:15]
	ds_read_b64_tr_b16 v[168:169], v204 offset:24576
	ds_read_b64_tr_b16 v[170:171], v205 offset:26624
	v_exp_f32_e32 v70, v70
	v_exp_f32_e32 v71, v71
	s_waitcnt lgkmcnt(14)
	v_mfma_f32_32x32x16_bf16 v[48:63], v[160:163], v[144:147], v[48:63]
	ds_read_b64_tr_b16 v[128:129], v210 offset:28672
	ds_read_b64_tr_b16 v[130:131], v211 offset:30720
	v_exp_f32_e32 v72, v72
	v_exp_f32_e32 v73, v73
	s_waitcnt lgkmcnt(14)
	v_mfma_f32_32x32x16_bf16 v[32:47], v[140:143], v[144:147], v[32:47]
	ds_read_b64_tr_b16 v[160:161], v208 offset:28672
	ds_read_b64_tr_b16 v[162:163], v209 offset:30720
	v_exp_f32_e32 v74, v74
	v_exp_f32_e32 v75, v75
	s_waitcnt lgkmcnt(14)
	v_mfma_f32_32x32x16_bf16 v[16:31], v[136:139], v[144:147], v[16:31]
	ds_read_b64_tr_b16 v[140:141], v206 offset:28672
	ds_read_b64_tr_b16 v[142:143], v207 offset:30720
	v_exp_f32_e32 v76, v76
	v_exp_f32_e32 v77, v77
	s_waitcnt lgkmcnt(14)
	v_mfma_f32_32x32x16_bf16 v[0:15], v[132:135], v[144:147], v[0:15]
	ds_read_b64_tr_b16 v[136:137], v204 offset:28672
	ds_read_b64_tr_b16 v[138:139], v205 offset:30720
	v_exp_f32_e32 v78, v78
	v_exp_f32_e32 v79, v79
	v_cvt_pk_bf16_f32 v132, v64, v65
	v_cvt_pk_bf16_f32 v133, v66, v67
	v_cvt_pk_bf16_f32 v134, v68, v69
	v_cvt_pk_bf16_f32 v135, v70, v71
	v_cvt_pk_bf16_f32 v144, v72, v73
	v_cvt_pk_bf16_f32 v145, v74, v75
	v_cvt_pk_bf16_f32 v146, v76, v77
	v_cvt_pk_bf16_f32 v147, v78, v79
	s_waitcnt lgkmcnt(14)
	v_mfma_f32_32x32x16_bf16 v[48:63], v[148:151], v[132:135], v[48:63]
	s_waitcnt lgkmcnt(12)
	v_mfma_f32_32x32x16_bf16 v[32:47], v[152:155], v[132:135], v[32:47]
	s_waitcnt lgkmcnt(10)
	v_mfma_f32_32x32x16_bf16 v[16:31], v[156:159], v[132:135], v[16:31]
	s_waitcnt lgkmcnt(8)
	v_mfma_f32_32x32x16_bf16 v[0:15], v[168:171], v[132:135], v[0:15]
	s_waitcnt lgkmcnt(6)
	v_mfma_f32_32x32x16_bf16 v[48:63], v[128:131], v[144:147], v[48:63]
	s_waitcnt lgkmcnt(4)
	v_mfma_f32_32x32x16_bf16 v[32:47], v[160:163], v[144:147], v[32:47]
	s_waitcnt lgkmcnt(2)
	v_mfma_f32_32x32x16_bf16 v[16:31], v[140:143], v[144:147], v[16:31]
	s_waitcnt lgkmcnt(0)
	v_mfma_f32_32x32x16_bf16 v[0:15], v[136:139], v[144:147], v[0:15]
	s_waitcnt vmcnt(0) lgkmcnt(0)
	s_barrier
; __device__ __forceinline__ void dattn_unit(const Args& a, unsigned char* ws, LAS unsigned char* lds, int l, int unit, int tid, int wid, int lane, int dry) {
;     ...
;     DA_STEP(31, 1, SB, SA, false, false, false);
	s_add_i32 s10, s54, 0xffffff86
	v_sub_u32_e32 v128, s54, v203
	s_cmp_lt_u32 s10, 0xffffff0d
	v_lshl_add_u32 v128, v128, 2, v212
	s_cbranch_scc1 .LBB0_657
	ds_read2_b32 v[130:131], v128 offset0:176 offset1:177
	ds_read2_b32 v[132:133], v128 offset0:178 offset1:179
	ds_read2_b32 v[134:135], v128 offset0:184 offset1:185
	ds_read2_b32 v[136:137], v128 offset0:186 offset1:187
	ds_read2_b32 v[138:139], v128 offset0:160 offset1:161
	ds_read2_b32 v[140:141], v128 offset0:162 offset1:163
	ds_read2_b32 v[142:143], v128 offset0:168 offset1:169
	ds_read2_b32 v[144:145], v128 offset0:170 offset1:171
	s_waitcnt lgkmcnt(4)
	v_pk_add_f32 v[126:127], v[126:127], v[136:137]
	v_pk_add_f32 v[124:125], v[124:125], v[134:135]
	v_pk_add_f32 v[122:123], v[122:123], v[132:133]
	v_pk_add_f32 v[120:121], v[120:121], v[130:131]
	s_waitcnt lgkmcnt(0)
	v_pk_add_f32 v[118:119], v[118:119], v[144:145]
	v_pk_add_f32 v[116:117], v[116:117], v[142:143]
	v_pk_add_f32 v[114:115], v[114:115], v[140:141]
	v_pk_add_f32 v[112:113], v[112:113], v[138:139]

; template <class Epi, class Sched, bool ALIGN_EPI = false, bool SP2 = false>
; __device__ __forceinline__ void gemm_phase(PG8_LAS unsigned char* lds, const Gemm g, const Sched& S, const Epi& E, const int tid) {
;     ...
;     f32x4 acc[2][2][4][2];
; #pragma unroll
;     for (int a = 0; a < 2; ++a)
; #pragma unroll
;         for (int b = 0; b < 2; ++b)
; #pragma unroll
;             for (int m = 0; m < 4; ++m)
; #pragma unroll
;                 for (int n = 0; n < 2; ++n) acc[a][b][m][n] = (f32x4){0.f, 0.f, 0.f, 0.f};
;     ...
; #pragma unroll
;         for (int a = 0; a < 2; ++a)
; #pragma unroll
;             for (int b = 0; b < 2; ++b)
; #pragma unroll
;                 for (int m = 0; m < 4; ++m)
; #pragma unroll
;                     for (int n = 0; n < 2; ++n) acc[a][b][m][n] = (f32x4){0.f, 0.f, 0.f, 0.f};
.LBB0_764:
	s_ashr_i32 s21, s20, 31
	s_lshl_b64 s[24:25], s[20:21], 19
	s_add_u32 s24, s36, s24
	s_addc_u32 s25, s37, s25
	s_and_b64 s[6:7], s[6:7], exec
	s_cselect_b32 s21, s25, s31
	s_cselect_b32 s58, s24, s30
	s_add_u32 s59, s30, 0x100
	v_mov_b64_e32 v[0:1], 0
	v_mov_b64_e32 v[2:3], 0
	v_mov_b64_e32 v[4:5], 0
	v_mov_b64_e32 v[6:7], 0
	v_mov_b64_e32 v[8:9], 0
	v_mov_b64_e32 v[10:11], 0
	v_mov_b64_e32 v[12:13], 0
	v_mov_b64_e32 v[14:15], 0
	v_mov_b64_e32 v[16:17], 0
	v_mov_b64_e32 v[18:19], 0
	v_mov_b64_e32 v[20:21], 0
	v_mov_b64_e32 v[22:23], 0
	v_mov_b64_e32 v[24:25], 0
	v_mov_b64_e32 v[26:27], 0
	v_mov_b64_e32 v[28:29], 0
	v_mov_b64_e32 v[30:31], 0
	v_mov_b64_e32 v[32:33], 0
	v_mov_b64_e32 v[34:35], 0
	v_mov_b64_e32 v[36:37], 0
	v_mov_b64_e32 v[38:39], 0
	v_mov_b64_e32 v[40:41], 0
	v_mov_b64_e32 v[42:43], 0
	v_mov_b64_e32 v[44:45], 0
	v_mov_b64_e32 v[46:47], 0
	v_mov_b64_e32 v[48:49], 0
	v_mov_b64_e32 v[50:51], 0
	v_mov_b64_e32 v[52:53], 0
	v_mov_b64_e32 v[54:55], 0
	v_mov_b64_e32 v[56:57], 0
	v_mov_b64_e32 v[58:59], 0
	v_mov_b64_e32 v[60:61], 0
	v_mov_b64_e32 v[62:63], 0
	v_mov_b64_e32 v[64:65], 0
	v_mov_b64_e32 v[66:67], 0
	v_mov_b64_e32 v[68:69], 0
	v_mov_b64_e32 v[70:71], 0
	v_mov_b64_e32 v[72:73], 0
	v_mov_b64_e32 v[74:75], 0
	v_mov_b64_e32 v[76:77], 0
	v_mov_b64_e32 v[78:79], 0
	v_mov_b64_e32 v[80:81], 0
	v_mov_b64_e32 v[82:83], 0
	v_mov_b64_e32 v[84:85], 0
	v_mov_b64_e32 v[86:87], 0
	v_mov_b64_e32 v[88:89], 0
	v_mov_b64_e32 v[90:91], 0
	v_mov_b64_e32 v[92:93], 0
	v_mov_b64_e32 v[94:95], 0
	v_mov_b64_e32 v[96:97], 0
	v_mov_b64_e32 v[98:99], 0
	v_mov_b64_e32 v[100:101], 0
	v_mov_b64_e32 v[102:103], 0
	v_mov_b64_e32 v[104:105], 0
	v_mov_b64_e32 v[106:107], 0
	v_mov_b64_e32 v[108:109], 0
	v_mov_b64_e32 v[110:111], 0
	v_mov_b64_e32 v[112:113], 0
	v_mov_b64_e32 v[114:115], 0
	v_mov_b64_e32 v[116:117], 0
	v_mov_b64_e32 v[118:119], 0
	v_mov_b64_e32 v[120:121], 0
	v_mov_b64_e32 v[122:123], 0
	v_mov_b64_e32 v[124:125], 0
	v_mov_b64_e32 v[126:127], 0
	s_addc_u32 s60, s31, 0
	s_mov_b32 s61, -2
	s_waitcnt lgkmcnt(0)

; template <class Epi, class Sched, bool ALIGN_EPI = false, bool SP2 = false>
; __device__ __forceinline__ void gemm_phase(PG8_LAS unsigned char* lds, const Gemm g, const Sched& S, const Epi& E, const int tid) {
;     ...
;     f32x4 acc[2][2][4][2];
; #pragma unroll
;     for (int a = 0; a < 2; ++a)
; #pragma unroll
;         for (int b = 0; b < 2; ++b)
; #pragma unroll
;             for (int m = 0; m < 4; ++m)
; #pragma unroll
;                 for (int n = 0; n < 2; ++n) acc[a][b][m][n] = (f32x4){0.f, 0.f, 0.f, 0.f};
;     ...
; #pragma unroll
;         for (int a = 0; a < 2; ++a)
; #pragma unroll
;             for (int b = 0; b < 2; ++b)
; #pragma unroll
;                 for (int m = 0; m < 4; ++m)
; #pragma unroll
;                     for (int n = 0; n < 2; ++n) acc[a][b][m][n] = (f32x4){0.f, 0.f, 0.f, 0.f};
.LBB0_922:
	s_add_u32 s61, s28, 0x100
	v_mov_b64_e32 v[0:1], 0
	v_mov_b64_e32 v[2:3], 0
	v_mov_b64_e32 v[4:5], 0
	v_mov_b64_e32 v[6:7], 0
	v_mov_b64_e32 v[8:9], 0
	v_mov_b64_e32 v[10:11], 0
	v_mov_b64_e32 v[12:13], 0
	v_mov_b64_e32 v[14:15], 0
	v_mov_b64_e32 v[16:17], 0
	v_mov_b64_e32 v[18:19], 0
	v_mov_b64_e32 v[20:21], 0
	v_mov_b64_e32 v[22:23], 0
	v_mov_b64_e32 v[24:25], 0
	v_mov_b64_e32 v[26:27], 0
	v_mov_b64_e32 v[28:29], 0
	v_mov_b64_e32 v[30:31], 0
	v_mov_b64_e32 v[32:33], 0
	v_mov_b64_e32 v[34:35], 0
	v_mov_b64_e32 v[36:37], 0
	v_mov_b64_e32 v[38:39], 0
	v_mov_b64_e32 v[40:41], 0
	v_mov_b64_e32 v[42:43], 0
	v_mov_b64_e32 v[44:45], 0
	v_mov_b64_e32 v[46:47], 0
	v_mov_b64_e32 v[48:49], 0
	v_mov_b64_e32 v[50:51], 0
	v_mov_b64_e32 v[52:53], 0
	v_mov_b64_e32 v[54:55], 0
	v_mov_b64_e32 v[56:57], 0
	v_mov_b64_e32 v[58:59], 0
	v_mov_b64_e32 v[60:61], 0
	v_mov_b64_e32 v[62:63], 0
	v_mov_b64_e32 v[64:65], 0
	v_mov_b64_e32 v[66:67], 0
	v_mov_b64_e32 v[68:69], 0
	v_mov_b64_e32 v[70:71], 0
	v_mov_b64_e32 v[72:73], 0
	v_mov_b64_e32 v[74:75], 0
	v_mov_b64_e32 v[76:77], 0
	v_mov_b64_e32 v[78:79], 0
	v_mov_b64_e32 v[80:81], 0
	v_mov_b64_e32 v[82:83], 0
	v_mov_b64_e32 v[84:85], 0
	v_mov_b64_e32 v[86:87], 0
	v_mov_b64_e32 v[88:89], 0
	v_mov_b64_e32 v[90:91], 0
	v_mov_b64_e32 v[92:93], 0
	v_mov_b64_e32 v[94:95], 0
	v_mov_b64_e32 v[96:97], 0
	v_mov_b64_e32 v[98:99], 0
	v_mov_b64_e32 v[100:101], 0
	v_mov_b64_e32 v[102:103], 0
	v_mov_b64_e32 v[104:105], 0
	v_mov_b64_e32 v[106:107], 0
	v_mov_b64_e32 v[108:109], 0
	v_mov_b64_e32 v[110:111], 0
	v_mov_b64_e32 v[112:113], 0
	v_mov_b64_e32 v[114:115], 0
	v_mov_b64_e32 v[116:117], 0
	v_mov_b64_e32 v[118:119], 0
	v_mov_b64_e32 v[120:121], 0
	v_mov_b64_e32 v[122:123], 0
	v_mov_b64_e32 v[124:125], 0
	v_mov_b64_e32 v[126:127], 0
	s_addc_u32 s62, s29, 0
	s_mov_b32 s63, -2
	s_waitcnt lgkmcnt(0)

; template <class Epi, class Sched, bool ALIGN_EPI = false, bool SP2 = false>
; __device__ __forceinline__ void gemm_phase(PG8_LAS unsigned char* lds, const Gemm g, const Sched& S, const Epi& E, const int tid) {
;     ...
;     f32x4 acc[2][2][4][2];
; #pragma unroll
;     for (int a = 0; a < 2; ++a)
; #pragma unroll
;         for (int b = 0; b < 2; ++b)
; #pragma unroll
;             for (int m = 0; m < 4; ++m)
; #pragma unroll
;                 for (int n = 0; n < 2; ++n) acc[a][b][m][n] = (f32x4){0.f, 0.f, 0.f, 0.f};
;     ...
; #pragma unroll
;         for (int a = 0; a < 2; ++a)
; #pragma unroll
;             for (int b = 0; b < 2; ++b)
; #pragma unroll
;                 for (int m = 0; m < 4; ++m)
; #pragma unroll
;                     for (int n = 0; n < 2; ++n) acc[a][b][m][n] = (f32x4){0.f, 0.f, 0.f, 0.f};
.LBB0_1006:
	s_ashr_i32 s19, s18, 31
	s_lshl_b64 s[20:21], s[18:19], 19
	s_add_u32 s20, s1, s20
	s_addc_u32 s21, s33, s21
	s_and_b64 s[22:23], s[2:3], exec
	s_cselect_b32 s19, s21, s27
	s_cselect_b32 s56, s20, s26
	s_ashr_i32 s17, s16, 31
	s_lshl_b64 s[22:23], s[16:17], 19
	s_add_u32 s22, s34, s22
	s_addc_u32 s23, s35, s23
	s_and_b64 s[30:31], s[2:3], exec
	s_cselect_b32 s17, s23, s29
	s_cselect_b32 s57, s22, s28
	s_add_u32 s26, s26, 0x40080
	s_addc_u32 s27, s27, 0
	s_add_u32 s58, s28, 0x100
	v_mov_b64_e32 v[0:1], 0
	v_mov_b64_e32 v[2:3], 0
	v_mov_b64_e32 v[4:5], 0
	v_mov_b64_e32 v[6:7], 0
	v_mov_b64_e32 v[8:9], 0
	v_mov_b64_e32 v[10:11], 0
	v_mov_b64_e32 v[12:13], 0
	v_mov_b64_e32 v[14:15], 0
	v_mov_b64_e32 v[16:17], 0
	v_mov_b64_e32 v[18:19], 0
	v_mov_b64_e32 v[20:21], 0
	v_mov_b64_e32 v[22:23], 0
	v_mov_b64_e32 v[24:25], 0
	v_mov_b64_e32 v[26:27], 0
	v_mov_b64_e32 v[28:29], 0
	v_mov_b64_e32 v[30:31], 0
	v_mov_b64_e32 v[32:33], 0
	v_mov_b64_e32 v[34:35], 0
	v_mov_b64_e32 v[36:37], 0
	v_mov_b64_e32 v[38:39], 0
	v_mov_b64_e32 v[40:41], 0
	v_mov_b64_e32 v[42:43], 0
	v_mov_b64_e32 v[44:45], 0
	v_mov_b64_e32 v[46:47], 0
	v_mov_b64_e32 v[48:49], 0
	v_mov_b64_e32 v[50:51], 0
	v_mov_b64_e32 v[52:53], 0
	v_mov_b64_e32 v[54:55], 0
	v_mov_b64_e32 v[56:57], 0
	v_mov_b64_e32 v[58:59], 0
	v_mov_b64_e32 v[60:61], 0
	v_mov_b64_e32 v[62:63], 0
	v_mov_b64_e32 v[64:65], 0
	v_mov_b64_e32 v[66:67], 0
	v_mov_b64_e32 v[68:69], 0
	v_mov_b64_e32 v[70:71], 0
	v_mov_b64_e32 v[72:73], 0
	v_mov_b64_e32 v[74:75], 0
	v_mov_b64_e32 v[76:77], 0
	v_mov_b64_e32 v[78:79], 0
	v_mov_b64_e32 v[80:81], 0
	v_mov_b64_e32 v[82:83], 0
	v_mov_b64_e32 v[84:85], 0
	v_mov_b64_e32 v[86:87], 0
	v_mov_b64_e32 v[88:89], 0
	v_mov_b64_e32 v[90:91], 0
	v_mov_b64_e32 v[92:93], 0
	v_mov_b64_e32 v[94:95], 0
	v_mov_b64_e32 v[96:97], 0
	v_mov_b64_e32 v[98:99], 0
	v_mov_b64_e32 v[100:101], 0
	v_mov_b64_e32 v[102:103], 0
	v_mov_b64_e32 v[104:105], 0
	v_mov_b64_e32 v[106:107], 0
	v_mov_b64_e32 v[108:109], 0
	v_mov_b64_e32 v[110:111], 0
	v_mov_b64_e32 v[112:113], 0
	v_mov_b64_e32 v[114:115], 0
	v_mov_b64_e32 v[116:117], 0
	v_mov_b64_e32 v[118:119], 0
	v_mov_b64_e32 v[120:121], 0
	v_mov_b64_e32 v[122:123], 0
	v_mov_b64_e32 v[124:125], 0
	v_mov_b64_e32 v[126:127], 0
	s_addc_u32 s59, s29, 0
	s_mov_b32 s60, -2
